# v12 + one static s_setprio 1 for waves 4-7 across the scan phase (reset to 0 at scan end)
# baseline (speedup 1.0000x reference)
.LBB0_417:
	s_or_b64 exec, exec, s[0:1]
	s_waitcnt lgkmcnt(0)
	s_barrier
	s_cmp_lt_u32 s65, 0x4000
	s_cbranch_scc1 .Lprio_skip
	s_setprio 1
.Lprio_skip:
	s_cmpk_gt_i32 s33, 0xff
	s_cbranch_scc1 .LBB0_619
	v_readlane_b32 s0, v254, 0
	v_readlane_b32 s1, v254, 1
	s_load_dwordx2 s[0:1], s[0:1], 0x58
	v_readlane_b32 s2, v255, 22
	v_readlane_b32 s3, v255, 23
	s_lshl_b64 s[2:3], s[2:3], 6
	s_mov_b32 s47, s93
	s_waitcnt lgkmcnt(0)
	s_add_u32 s0, s0, s2
	s_addc_u32 s1, s1, s3
	v_writelane_b32 v255, s0, 37
	s_nop 1
	v_writelane_b32 v255, s1, 38
	s_and_b32 s0, s33, 1
	s_lshl_b32 s1, s0, 3
	v_writelane_b32 v255, s1, 39
	s_mul_i32 s1, s0, 0x8800
	s_bitcmp1_b32 s33, 0
	v_writelane_b32 v255, s1, 41
	s_cselect_b64 s[2:3], -1, 0
	v_writelane_b32 v255, s2, 43
	s_nop 1
	v_writelane_b32 v255, s3, 44
	s_lshl_b32 s2, s0, 7
	s_cmp_eq_u32 s0, 0
	s_cselect_b64 s[4:5], -1, 0
	s_mov_b32 s3, s93
	s_and_b64 s[0:1], s[4:5], exec
	v_writelane_b32 v255, s2, 45
	s_cselect_b32 s46, 0x7f, 0
	s_lshl_b32 s0, s2, 2
	v_writelane_b32 v255, s3, 46
	v_writelane_b32 v255, s0, 47
	s_mov_b32 s1, s33
	v_writelane_b32 v255, s33, 30
	s_branch .LBB0_420

.LBB0_619:
	s_setprio 0
	v_readlane_b32 s0, v254, 2
	v_readlane_b32 s2, v254, 4
	v_readlane_b32 s3, v254, 5
	s_mov_b64 s[36:37], s[2:3]
	v_readlane_b32 s18, v254, 6
	s_waitcnt vmcnt(0)
	v_readlane_b32 s1, v254, 3
	s_barrier
	s_mov_b64 s[0:1], exec
	v_readlane_b32 s2, v254, 7
	v_readlane_b32 s3, v254, 8
	s_and_b64 s[2:3], s[0:1], s[2:3]
	s_mov_b64 exec, s[2:3]
	s_cbranch_execz .LBB0_663
	v_readlane_b32 s2, v255, 20
	s_waitcnt vmcnt(0) expcnt(0) lgkmcnt(0)
	s_nop 0
	v_mov_b32_e32 v1, s2
	ds_read_b32 v4, v1
	v_readlane_b32 s2, v255, 21
	s_waitcnt lgkmcnt(0)
	v_cmp_ne_u32_e32 vcc, 0, v4
	v_mov_b32_e32 v1, s2
	ds_read_b32 v2, v1
	s_cbranch_vccnz .LBB0_634
	v_readlane_b32 s2, v254, 46
	v_readlane_b32 s3, v254, 47
	s_load_dwordx2 s[6:7], s[2:3], 0x0
	s_load_dword s5, s[2:3], 0x8
	s_add_u32 s2, s36, 0x1000
	s_addc_u32 s3, s37, 0
	s_add_u32 s4, s36, 0x1100
	s_waitcnt lgkmcnt(0)
	s_mul_i32 s19, s7, s6
	s_mul_i32 s19, s19, s5
	s_addc_u32 s5, s37, 0
	s_add_u32 s6, s36, 0x1200
	s_addc_u32 s7, s37, 0
	s_add_u32 s8, s36, 0x1300
	s_addc_u32 s9, s37, 0
	s_mov_b32 s30, 1
	s_mov_b64 s[10:11], 0
	s_branch .LBB0_624
